# GEMM phase prologue de-serialisation: K-tile 1's six LDS-DMA issued together with K-tile 0's eight, before the first wait (vmcnt 2 -> 8)
# speedup vs baseline: 1.0018x; 1.0018x over previous
; #define PG8_STAGE(bufoff, gbase, voff) do { _Pragma("unroll") for (int _i = 0; _i < 2; ++_i) \
;         __builtin_amdgcn_global_load_lds((const unsigned*)((const char*)(gbase) + (voff)[_i]), (LAS unsigned*)(lds + (bufoff) + ldsw + _i * 8192), 16, 0, 0); } while (0)
; #define PG8_WAIT_V(n) asm volatile("s_waitcnt vmcnt(" #n ")" ::: "memory")
; #define PG8_BAR __builtin_amdgcn_s_barrier()
; template <class Epi, class Sched, int LDA, int LDB, bool ALIGN_EPI = true>
; __device__ __forceinline__ void gemm_phase(LAS unsigned char* lds, const Gemm g, const Sched& S, const Epi& E, int wave) {
;     ...
;     const char* cA = (const char*)g.A + (size_t)cur.pm * tstepA + (size_t)cur.kofs * 2; const char* cB = (const char*)g.Bt + (size_t)cur.pn * tstepB + (size_t)cur.kofs * 2;
;     PG8_STAGE(PG8_SB(0, 0), cB, voffB); PG8_STAGE(PG8_SB(0, 1), cB + hstepB, voffB); PG8_STAGE(PG8_SA(0, 0), cA, voffA); PG8_STAGE(PG8_SA(0, 1), cA + hstepA, voffA);
;     if (wr == 1) PG8_BAR;
;     PG8_WAIT_V(2); PG8_BAR;
;     PG8_STAGE(PG8_SB(1, 0), cB + kstep, voffB); PG8_STAGE(PG8_SA(1, 0), cA + kstep, voffA); PG8_STAGE(PG8_SB(1, 1), cB + hstepB + kstep, voffB);
;     PG8_WAIT_V(6); PG8_BAR;
.LBB0_477:
	v_and_b32_e32 v19, 15, v18
	v_readlane_b32 s0, v252, 8
	v_lshrrev_b32_e32 v20, 1, v18
	v_and_b32_e32 v20, 24, v20
	v_or_b32_e32 v142, s0, v19
	v_lshlrev_b32_e32 v21, 6, v142
	v_lshlrev_b32_e32 v22, 1, v20
	s_movk_i32 s0, 0x3c0
	v_lshlrev_b32_e32 v23, 2, v142
	v_and_or_b32 v21, v21, s0, v22
	v_and_b32_e32 v23, 32, v23
	v_readlane_b32 s0, v252, 9
	v_lshlrev_b32_e32 v18, 2, v18
	v_lshl_or_b32 v19, v19, 6, v22
	v_bitop3_b32 v21, v21, s0, v23 bitop3:0xde
	v_and_b32_e32 v18, 32, v18
	v_readlane_b32 s0, v252, 11
	s_add_i32 m0, s38, 0x18000
	s_nop 1
	v_bitop3_b32 v143, v19, s0, v18 bitop3:0xde
	s_mov_b64 s[0:1], 0x80
	v_lshl_add_u64 v[2:3], v[2:3], 0, s[0:1]
	global_load_lds_dwordx4 v[2:3], off
	v_lshl_add_u64 v[2:3], v[4:5], 0, s[0:1]
	s_add_i32 m0, s38, 0x1a000
	s_add_i32 s48, s38, 0x8000
	global_load_lds_dwordx4 v[2:3], off
	v_lshl_add_u64 v[2:3], v[6:7], 0, s[0:1]
	s_mov_b32 m0, s48
	s_add_i32 s49, s38, 0xa000
	global_load_lds_dwordx4 v[2:3], off
	v_lshl_add_u64 v[2:3], v[8:9], 0, s[0:1]
	s_add_u32 s0, s24, 0x80080
	s_mov_b32 m0, s49
	s_addc_u32 s1, s25, 0
	global_load_lds_dwordx4 v[2:3], off
	v_lshl_add_u64 v[2:3], s[0:1], 0, v[0:1]
	s_add_i32 m0, s38, 0x1c000
	s_movk_i32 s2, 0x840
	global_load_lds_dwordx4 v[2:3], off
	v_lshl_add_u64 v[2:3], s[0:1], 0, v[130:131]
	s_add_i32 m0, s38, 0x1e000
	v_readlane_b32 s0, v252, 10
	global_load_lds_dwordx4 v[2:3], off
	s_waitcnt vmcnt(8)
	s_barrier
	v_lshrrev_b32_e32 v3, 1, v14
	v_mul_lo_u32 v2, v15, s2
	s_mov_b32 s3, 0x8400
	v_or_b32_e32 v144, s0, v20
	v_mad_u64_u32 v[2:3], s[0:1], v3, s3, v[2:3]
	v_or_b32_e32 v2, v2, v16
	v_add_lshl_u32 v2, v2, v17, 1
	v_mov_b32_e32 v3, v1
	s_mov_b64 s[6:7], 0x84080
	v_lshl_add_u64 v[136:137], v[2:3], 0, s[6:7]
	v_lshrrev_b32_e32 v3, 1, v10
	v_mul_lo_u32 v2, v11, s2
	v_mad_u64_u32 v[2:3], s[0:1], v3, s3, v[2:3]
	s_waitcnt vmcnt(6)
	v_or_b32_e32 v2, v2, v12
	v_add_lshl_u32 v2, v2, v13, 1
	v_mov_b32_e32 v3, v1
	v_lshl_add_u64 v[138:139], v[2:3], 0, s[6:7]
	s_mov_b32 s50, 0
	v_add_u32_e32 v145, 0, v21
	s_barrier
	s_branch .LBB0_480

; #define PG8_STAGE(bufoff, gbase, voff) do { _Pragma("unroll") for (int _i = 0; _i < 2; ++_i) \
;         __builtin_amdgcn_global_load_lds((const unsigned*)((const char*)(gbase) + (voff)[_i]), (LAS unsigned*)(lds + (bufoff) + ldsw + _i * 8192), 16, 0, 0); } while (0)
; #define PG8_WAIT_V(n) asm volatile("s_waitcnt vmcnt(" #n ")" ::: "memory")
; #define PG8_BAR __builtin_amdgcn_s_barrier()
; template <class Epi, class Sched, int LDA, int LDB, bool ALIGN_EPI = true>
; __device__ __forceinline__ void gemm_phase(LAS unsigned char* lds, const Gemm g, const Sched& S, const Epi& E, int wave) {
;     ...
;     const char* cA = (const char*)g.A + (size_t)cur.pm * tstepA + (size_t)cur.kofs * 2; const char* cB = (const char*)g.Bt + (size_t)cur.pn * tstepB + (size_t)cur.kofs * 2;
;     PG8_STAGE(PG8_SB(0, 0), cB, voffB); PG8_STAGE(PG8_SB(0, 1), cB + hstepB, voffB); PG8_STAGE(PG8_SA(0, 0), cA, voffA); PG8_STAGE(PG8_SA(0, 1), cA + hstepA, voffA);
;     if (wr == 1) PG8_BAR;
;     PG8_WAIT_V(2); PG8_BAR;
;     PG8_STAGE(PG8_SB(1, 0), cB + kstep, voffB); PG8_STAGE(PG8_SA(1, 0), cA + kstep, voffA); PG8_STAGE(PG8_SB(1, 1), cB + hstepB + kstep, voffB);
;     PG8_WAIT_V(6); PG8_BAR;
.LBB0_1874:
	s_lshl_b32 s12, s12, 2
	v_readlane_b32 s0, v254, 62
	v_readlane_b32 s1, v254, 63
	s_add_u32 s54, s0, s12
	s_addc_u32 s55, s1, 0
	s_and_b64 s[10:11], s[10:11], exec
	s_cselect_b32 s95, 0, s21
	s_cselect_b32 s94, 0, s20
	s_and_b64 s[8:9], s[8:9], exec
	v_readlane_b32 s0, v250, 10
	v_readlane_b32 s2, v250, 12
	v_readlane_b32 s3, v250, 13
	v_readlane_b32 s12, v250, 22
	v_readlane_b32 s2, v254, 60
	s_mul_i32 s12, s2, 3
	v_and_b32_e32 v19, 15, v10
	v_readlane_b32 s2, v252, 8
	v_bfe_u32 v20, v10, 4, 2
	v_lshlrev_b32_e32 v22, 4, v20
	v_or_b32_e32 v248, s2, v19
	v_lshlrev_b32_e32 v21, 6, v248
	s_movk_i32 s2, 0x3c0
	v_lshlrev_b32_e32 v23, 2, v248
	v_and_or_b32 v21, v21, s2, v22
	v_and_b32_e32 v23, 32, v23
	v_readlane_b32 s2, v252, 9
	v_lshlrev_b32_e32 v10, 2, v10
	v_readlane_b32 s3, v254, 61
	v_bitop3_b32 v21, v21, s2, v23 bitop3:0xde
	v_lshl_or_b32 v19, v19, 6, v22
	v_and_b32_e32 v10, 32, v10
	v_readlane_b32 s2, v252, 11
	v_readlane_b32 s1, v250, 11
	v_readlane_b32 s5, v250, 15
	v_bitop3_b32 v249, v19, s2, v10 bitop3:0xde
	s_mov_b64 s[2:3], 0x80
	v_readlane_b32 s14, v250, 24
	s_cselect_b32 s1, s1, 0
	s_cselect_b32 s0, s0, 0
	s_lshl_b32 s5, s77, 1
	v_lshl_add_u64 v[2:3], v[2:3], 0, s[2:3]
	s_add_i32 m0, s50, 0x18000
	s_add_i32 s14, s12, s5
	s_nop 1
	global_load_lds_dwordx4 v[2:3], off
	v_lshl_add_u64 v[2:3], v[4:5], 0, s[2:3]
	s_add_i32 m0, s50, 0x1a000
	s_add_i32 s5, s50, 0x8000
	s_add_i32 s59, s50, 0xa000
	v_readlane_b32 s13, v250, 23
	global_load_lds_dwordx4 v[2:3], off
	v_lshl_add_u64 v[2:3], v[6:7], 0, s[2:3]
	s_mov_b32 m0, s5
	s_add_u32 s12, s38, 0x160080
	global_load_lds_dwordx4 v[2:3], off
	v_lshl_add_u64 v[2:3], v[8:9], 0, s[2:3]
	s_mov_b32 m0, s59
	s_addc_u32 s13, s39, 0
	global_load_lds_dwordx4 v[2:3], off
	v_lshl_add_u64 v[2:3], s[12:13], 0, v[0:1]
	s_add_i32 m0, s50, 0x1c000
	v_readlane_b32 s2, v252, 41
	global_load_lds_dwordx4 v[2:3], off
	v_lshl_add_u64 v[2:3], s[12:13], 0, v[142:143]
	s_add_i32 m0, s50, 0x1e000
	s_lshl_b32 s12, s14, 15
	global_load_lds_dwordx4 v[2:3], off
	s_waitcnt vmcnt(8)
	s_barrier
	s_add_u32 s12, s2, s12
	v_readlane_b32 s2, v252, 42
	s_addc_u32 s13, s2, 0
	v_readlane_b32 s2, v252, 10
	s_movk_i32 s3, 0x1600
	v_lshrrev_b32_e32 v3, 1, v11
	v_lshl_or_b32 v234, v20, 3, s2
	v_mul_lo_u32 v2, v13, s3
	s_mov_b32 s2, 0x16000
	v_mad_u64_u32 v[2:3], s[24:25], v3, s2, v[2:3]
	v_readlane_b32 s6, v250, 16
	v_readlane_b32 s7, v250, 17
	v_or_b32_e32 v2, v2, v12
	v_add_lshl_u32 v2, v2, v14, 1
	v_mov_b32_e32 v3, v1
	s_mov_b64 s[6:7], 0x160080
	s_lshl_b32 s64, s14, 5
	v_lshl_add_u64 v[144:145], v[2:3], 0, s[6:7]
	v_lshrrev_b32_e32 v3, 1, v15
	v_mul_lo_u32 v2, v17, s3
	v_readlane_b32 s15, v250, 25
	s_cmp_eq_u64 s[94:95], 0
	v_mad_u64_u32 v[2:3], s[24:25], v3, s2, v[2:3]
	s_waitcnt vmcnt(6)
	s_cselect_b64 s[14:15], -1, 0
	s_cmp_lg_u64 s[94:95], 0
	v_or_b32_e32 v2, v2, v16
	v_readlane_b32 s4, v250, 14
	s_cselect_b64 s[16:17], -1, 0
	s_cmp_lg_u64 s[0:1], 0
	v_add_lshl_u32 v2, v2, v18, 1
	v_mov_b32_e32 v3, v1
	s_mov_b32 s58, 0
	v_cmp_eq_u32_e64 s[42:43], 0, v20
	s_cselect_b64 s[18:19], -1, 0
	v_lshl_add_u64 v[146:147], v[2:3], 0, s[6:7]
	v_add_u32_e32 v236, 0, v21
	v_readlane_b32 s4, v250, 52
	v_readlane_b32 s6, v250, 53
	v_readlane_b32 s8, v250, 18
	v_readlane_b32 s9, v250, 19
	v_readlane_b32 s10, v250, 20
	v_readlane_b32 s11, v250, 21
	s_barrier
	s_branch .LBB0_1877

; #define PG8_STAGE(bufoff, gbase, voff) do { _Pragma("unroll") for (int _i = 0; _i < 2; ++_i) \
;         __builtin_amdgcn_global_load_lds((const unsigned*)((const char*)(gbase) + (voff)[_i]), (LAS unsigned*)(lds + (bufoff) + ldsw + _i * 8192), 16, 0, 0); } while (0)
; #define PG8_WAIT_V(n) asm volatile("s_waitcnt vmcnt(" #n ")" ::: "memory")
; #define PG8_BAR __builtin_amdgcn_s_barrier()
; template <class Epi, class Sched, int LDA, int LDB, bool ALIGN_EPI = true>
; __device__ __forceinline__ void gemm_phase(LAS unsigned char* lds, const Gemm g, const Sched& S, const Epi& E, int wave) {
;     ...
;     const char* cA = (const char*)g.A + (size_t)cur.pm * tstepA + (size_t)cur.kofs * 2; const char* cB = (const char*)g.Bt + (size_t)cur.pn * tstepB + (size_t)cur.kofs * 2;
;     PG8_STAGE(PG8_SB(0, 0), cB, voffB); PG8_STAGE(PG8_SB(0, 1), cB + hstepB, voffB); PG8_STAGE(PG8_SA(0, 0), cA, voffA); PG8_STAGE(PG8_SA(0, 1), cA + hstepA, voffA);
;     if (wr == 1) PG8_BAR;
;     PG8_WAIT_V(2); PG8_BAR;
;     PG8_STAGE(PG8_SB(1, 0), cB + kstep, voffB); PG8_STAGE(PG8_SA(1, 0), cA + kstep, voffA); PG8_STAGE(PG8_SB(1, 1), cB + hstepB + kstep, voffB);
;     PG8_WAIT_V(6); PG8_BAR;
.LBB0_2237:
	s_mov_b64 s[8:9], 0x80
	v_lshl_add_u64 v[2:3], v[2:3], 0, s[8:9]
	s_add_i32 m0, s19, 0x18000
	s_nop 1
	global_load_lds_dwordx4 v[2:3], off
	v_lshl_add_u64 v[2:3], v[4:5], 0, s[8:9]
	s_add_i32 m0, s19, 0x1a000
	s_add_i32 s38, s19, 0x8000
	global_load_lds_dwordx4 v[2:3], off
	v_lshl_add_u64 v[2:3], v[6:7], 0, s[8:9]
	s_mov_b32 m0, s38
	s_add_i32 s39, s19, 0xa000
	global_load_lds_dwordx4 v[2:3], off
	v_lshl_add_u64 v[2:3], v[8:9], 0, s[8:9]
	s_add_u32 s8, s2, 0x80080
	s_mov_b32 m0, s39
	s_addc_u32 s9, s3, 0
	global_load_lds_dwordx4 v[2:3], off
	v_lshl_add_u64 v[2:3], s[8:9], 0, v[132:133]
	s_add_i32 m0, s19, 0x1c000
	v_and_b32_e32 v160, 15, v0
	global_load_lds_dwordx4 v[2:3], off
	v_lshl_add_u64 v[2:3], s[8:9], 0, v[136:137]
	s_add_i32 m0, s19, 0x1e000
	v_readlane_b32 s7, v252, 8
	global_load_lds_dwordx4 v[2:3], off
	s_waitcnt vmcnt(8)
	s_barrier
	v_bfe_u32 v18, v0, 4, 2
	v_or_b32_e32 v19, s7, v160
	v_lshlrev_b32_e32 v20, 6, v19
	v_lshlrev_b32_e32 v21, 4, v18
	s_movk_i32 s7, 0x3c0
	v_lshlrev_b32_e32 v19, 2, v19
	v_and_or_b32 v20, v20, s7, v21
	v_and_b32_e32 v19, 32, v19
	v_readlane_b32 s7, v252, 9
	v_readlane_b32 s8, v254, 20
	s_movk_i32 s14, 0x840
	v_bitop3_b32 v19, v20, s7, v19 bitop3:0xde
	v_lshl_or_b32 v20, v160, 6, v21
	v_lshlrev_b32_e32 v21, 2, v0
	v_lshlrev_b32_e32 v0, 1, v0
	v_and_b32_e32 v0, 32, v0
	v_add_u32_e32 v162, s8, v0
	v_lshrrev_b32_e32 v2, 1, v10
	v_mul_lo_u32 v0, v12, s14
	s_mov_b32 s15, 0x8400
	s_lshr_b32 s51, s6, 3
	v_mad_u64_u32 v[2:3], s[12:13], v2, s15, v[0:1]
	s_and_b32 s52, s6, 6
	s_add_i32 s53, s51, 1
	s_mul_i32 s10, s68, 0x8800
	v_or_b32_e32 v0, v2, v11
	s_add_u32 s8, s22, s10
	v_add_lshl_u32 v0, v0, v13, 1
	s_mov_b64 s[16:17], 0x84080
	s_addc_u32 s9, s23, 0
	v_lshl_add_u64 v[140:141], v[0:1], 0, s[16:17]
	v_lshrrev_b32_e32 v2, 1, v14
	v_mul_lo_u32 v0, v16, s14
	s_add_u32 s8, s8, 0x88800
	v_mad_u64_u32 v[2:3], s[12:13], v2, s15, v[0:1]
	v_and_b32_e32 v21, 32, v21
	v_readlane_b32 s7, v252, 46
	s_waitcnt vmcnt(6)
	s_addc_u32 s9, s9, 0
	v_readlane_b32 s11, v252, 54
	v_or_b32_e32 v0, v2, v15
	v_bitop3_b32 v161, v20, s7, v21 bitop3:0xde
	v_readlane_b32 s7, v252, 45
	s_add_u32 s10, s11, s10
	v_readlane_b32 s11, v252, 55
	v_add_lshl_u32 v0, v0, v17, 1
	v_lshl_or_b32 v138, v18, 3, s7
	v_mov_b32_e32 v139, v1
	v_cmp_gt_u32_e64 s[42:43], 2, v18
	s_mov_b32 s50, 0
	v_cmp_eq_u32_e64 s[44:45], 0, v18
	s_mov_b32 s7, s97
	s_addc_u32 s11, s11, 0
	v_lshl_add_u64 v[142:143], v[0:1], 0, s[16:17]
	v_add_u32_e32 v163, 0, v19
	s_barrier
	s_branch .LBB0_2240

; #define PG8_STAGE(bufoff, gbase, voff) do { _Pragma("unroll") for (int _i = 0; _i < 2; ++_i) \
;         __builtin_amdgcn_global_load_lds((const unsigned*)((const char*)(gbase) + (voff)[_i]), (LAS unsigned*)(lds + (bufoff) + ldsw + _i * 8192), 16, 0, 0); } while (0)
; #define PG8_WAIT_V(n) asm volatile("s_waitcnt vmcnt(" #n ")" ::: "memory")
; #define PG8_BAR __builtin_amdgcn_s_barrier()
; template <class Epi, class Sched, int LDA, int LDB, bool ALIGN_EPI = true>
; __device__ __forceinline__ void gemm_phase(LAS unsigned char* lds, const Gemm g, const Sched& S, const Epi& E, int wave) {
;     ...
;     const char* cA = (const char*)g.A + (size_t)cur.pm * tstepA + (size_t)cur.kofs * 2; const char* cB = (const char*)g.Bt + (size_t)cur.pn * tstepB + (size_t)cur.kofs * 2;
;     PG8_STAGE(PG8_SB(0, 0), cB, voffB); PG8_STAGE(PG8_SB(0, 1), cB + hstepB, voffB); PG8_STAGE(PG8_SA(0, 0), cA, voffA); PG8_STAGE(PG8_SA(0, 1), cA + hstepA, voffA);
;     if (wr == 1) PG8_BAR;
;     PG8_WAIT_V(2); PG8_BAR;
;     PG8_STAGE(PG8_SB(1, 0), cB + kstep, voffB); PG8_STAGE(PG8_SA(1, 0), cA + kstep, voffA); PG8_STAGE(PG8_SB(1, 1), cB + hstepB + kstep, voffB);
;     PG8_WAIT_V(6); PG8_BAR;
.LBB0_2403:
	v_and_b32_e32 v9, 15, v8
	v_readlane_b32 s1, v252, 8
	v_lshrrev_b32_e32 v18, 1, v8
	v_and_b32_e32 v18, 24, v18
	v_or_b32_e32 v142, s1, v9
	v_lshlrev_b32_e32 v19, 6, v142
	v_lshlrev_b32_e32 v20, 1, v18
	s_movk_i32 s1, 0x3c0
	v_lshlrev_b32_e32 v21, 2, v142
	v_and_or_b32 v19, v19, s1, v20
	v_and_b32_e32 v21, 32, v21
	v_readlane_b32 s1, v252, 9
	v_lshlrev_b32_e32 v8, 2, v8
	v_lshl_add_u64 v[10:11], s[12:13], 0, v[0:1]
	v_mov_b32_e32 v135, v1
	v_bitop3_b32 v19, v19, s1, v21 bitop3:0xde
	v_lshl_or_b32 v9, v9, 6, v20
	v_and_b32_e32 v8, 32, v8
	v_readlane_b32 s1, v252, 11
	s_mov_b64 s[2:3], 0x80
	v_lshl_add_u64 v[12:13], s[12:13], 0, v[134:135]
	v_mov_b32_e32 v131, v1
	v_bitop3_b32 v143, v9, s1, v8 bitop3:0xde
	v_lshl_add_u64 v[8:9], v[10:11], 0, s[2:3]
	s_add_i32 m0, s18, 0x18000
	v_lshl_add_u64 v[14:15], s[10:11], 0, v[130:131]
	v_mov_b32_e32 v133, v1
	s_nop 1
	global_load_lds_dwordx4 v[8:9], off
	v_lshl_add_u64 v[8:9], v[12:13], 0, s[2:3]
	s_add_i32 m0, s18, 0x1a000
	s_add_i32 s26, s18, 0x8000
	v_lshl_add_u64 v[16:17], s[10:11], 0, v[132:133]
	global_load_lds_dwordx4 v[8:9], off
	v_lshl_add_u64 v[8:9], v[14:15], 0, s[2:3]
	s_mov_b32 m0, s26
	s_add_i32 s27, s18, 0xa000
	global_load_lds_dwordx4 v[8:9], off
	v_lshl_add_u64 v[8:9], v[16:17], 0, s[2:3]
	s_add_u32 s2, s12, 0x84080
	s_mov_b32 m0, s27
	s_addc_u32 s3, s13, 0
	global_load_lds_dwordx4 v[8:9], off
	v_lshl_add_u64 v[8:9], s[2:3], 0, v[0:1]
	s_add_i32 m0, s18, 0x1c000
	v_readlane_b32 s1, v252, 10
	global_load_lds_dwordx4 v[8:9], off
	v_lshl_add_u64 v[8:9], s[2:3], 0, v[134:135]
	s_add_i32 m0, s18, 0x1e000
	s_ashr_i32 s28, s4, 31
	global_load_lds_dwordx4 v[8:9], off
	s_waitcnt vmcnt(8)
	s_barrier
	v_lshlrev_b32_e32 v8, 15, v2
	v_and_b32_e32 v8, 0xffff0000, v8
	v_lshl_add_u32 v3, v3, 12, v8
	v_and_b32_e32 v2, 1, v2
	v_lshl_or_b32 v2, v2, 6, v3
	v_lshl_add_u32 v136, v4, 1, v2
	v_lshlrev_b32_e32 v2, 15, v5
	v_and_b32_e32 v2, 0xffff0000, v2
	s_waitcnt vmcnt(6)
	v_lshl_add_u32 v2, v6, 12, v2
	v_and_b32_e32 v3, 1, v5
	v_lshl_or_b32 v2, v3, 6, v2
	v_or_b32_e32 v144, s1, v18
	v_mov_b32_e32 v137, v1
	v_lshl_add_u32 v138, v7, 1, v2
	v_mov_b32_e32 v139, v1
	s_mov_b32 s29, 0
	v_add_u32_e32 v145, 0, v19
	s_barrier
	s_branch .LBB0_2406

; #define PG8_STAGE(bufoff, gbase, voff) do { _Pragma("unroll") for (int _i = 0; _i < 2; ++_i) \
;         __builtin_amdgcn_global_load_lds((const unsigned*)((const char*)(gbase) + (voff)[_i]), (LAS unsigned*)(lds + (bufoff) + ldsw + _i * 8192), 16, 0, 0); } while (0)
; #define PG8_WAIT_V(n) asm volatile("s_waitcnt vmcnt(" #n ")" ::: "memory")
; #define PG8_BAR __builtin_amdgcn_s_barrier()
; template <class Epi, class Sched, int LDA, int LDB, bool ALIGN_EPI = true>
; __device__ __forceinline__ void gemm_phase(LAS unsigned char* lds, const Gemm g, const Sched& S, const Epi& E, int wave) {
;     ...
;     const char* cA = (const char*)g.A + (size_t)cur.pm * tstepA + (size_t)cur.kofs * 2; const char* cB = (const char*)g.Bt + (size_t)cur.pn * tstepB + (size_t)cur.kofs * 2;
;     PG8_STAGE(PG8_SB(0, 0), cB, voffB); PG8_STAGE(PG8_SB(0, 1), cB + hstepB, voffB); PG8_STAGE(PG8_SA(0, 0), cA, voffA); PG8_STAGE(PG8_SA(0, 1), cA + hstepA, voffA);
;     if (wr == 1) PG8_BAR;
;     PG8_WAIT_V(2); PG8_BAR;
;     PG8_STAGE(PG8_SB(1, 0), cB + kstep, voffB); PG8_STAGE(PG8_SA(1, 0), cA + kstep, voffA); PG8_STAGE(PG8_SB(1, 1), cB + hstepB + kstep, voffB);
;     PG8_WAIT_V(6); PG8_BAR;
.LBB0_2501:
	v_and_b32_e32 v9, 15, v8
	v_readlane_b32 s1, v252, 8
	v_lshrrev_b32_e32 v18, 1, v8
	v_and_b32_e32 v18, 24, v18
	v_or_b32_e32 v142, s1, v9
	v_lshlrev_b32_e32 v19, 6, v142
	v_lshlrev_b32_e32 v20, 1, v18
	s_movk_i32 s1, 0x3c0
	v_lshlrev_b32_e32 v21, 2, v142
	v_and_or_b32 v19, v19, s1, v20
	v_and_b32_e32 v21, 32, v21
	v_readlane_b32 s1, v252, 9
	v_lshlrev_b32_e32 v8, 2, v8
	v_lshl_add_u64 v[10:11], s[14:15], 0, v[0:1]
	v_mov_b32_e32 v135, v1
	v_bitop3_b32 v19, v19, s1, v21 bitop3:0xde
	v_lshl_or_b32 v9, v9, 6, v20
	v_and_b32_e32 v8, 32, v8
	v_readlane_b32 s1, v252, 11
	v_lshl_add_u64 v[12:13], s[14:15], 0, v[134:135]
	v_mov_b32_e32 v131, v1
	v_bitop3_b32 v143, v9, s1, v8 bitop3:0xde
	v_lshl_add_u64 v[8:9], v[10:11], 0, s[72:73]
	s_add_i32 m0, s24, 0x18000
	v_lshl_add_u64 v[14:15], s[12:13], 0, v[130:131]
	v_mov_b32_e32 v133, v1
	s_nop 1
	global_load_lds_dwordx4 v[8:9], off
	v_lshl_add_u64 v[8:9], v[12:13], 0, s[72:73]
	s_add_i32 m0, s24, 0x1a000
	s_add_i32 s28, s24, 0x8000
	s_add_i32 s29, s24, 0xa000
	v_lshl_add_u64 v[16:17], s[12:13], 0, v[132:133]
	global_load_lds_dwordx4 v[8:9], off
	v_lshl_add_u64 v[8:9], v[14:15], 0, s[72:73]
	s_mov_b32 m0, s28
	s_add_u32 s2, s14, 0x84080
	global_load_lds_dwordx4 v[8:9], off
	v_lshl_add_u64 v[8:9], v[16:17], 0, s[72:73]
	s_mov_b32 m0, s29
	s_addc_u32 s3, s15, 0
	global_load_lds_dwordx4 v[8:9], off
	v_lshl_add_u64 v[8:9], s[2:3], 0, v[0:1]
	s_add_i32 m0, s24, 0x1c000
	v_readlane_b32 s1, v252, 10
	global_load_lds_dwordx4 v[8:9], off
	v_lshl_add_u64 v[8:9], s[2:3], 0, v[134:135]
	s_add_i32 m0, s24, 0x1e000
	v_or_b32_e32 v144, s1, v18
	global_load_lds_dwordx4 v[8:9], off
	s_waitcnt vmcnt(8)
	s_barrier
	v_lshlrev_b32_e32 v8, 15, v2
	v_and_b32_e32 v8, 0xffff0000, v8
	v_lshl_add_u32 v3, v3, 12, v8
	v_and_b32_e32 v2, 1, v2
	v_lshl_or_b32 v2, v2, 6, v3
	v_lshl_add_u32 v136, v4, 1, v2
	v_lshlrev_b32_e32 v2, 15, v5
	v_and_b32_e32 v2, 0xffff0000, v2
	s_waitcnt vmcnt(6)
	v_lshl_add_u32 v2, v6, 12, v2
	v_and_b32_e32 v3, 1, v5
	v_lshl_or_b32 v2, v3, 6, v2
	v_mov_b32_e32 v137, v1
	v_lshl_add_u32 v138, v7, 1, v2
	v_mov_b32_e32 v139, v1
	s_mov_b32 s34, 0
	v_add_u32_e32 v145, 0, v19
	s_barrier
	s_branch .LBB0_2504

; #define PG8_STAGE(bufoff, gbase, voff) do { _Pragma("unroll") for (int _i = 0; _i < 2; ++_i) \
;         __builtin_amdgcn_global_load_lds((const unsigned*)((const char*)(gbase) + (voff)[_i]), (LAS unsigned*)(lds + (bufoff) + ldsw + _i * 8192), 16, 0, 0); } while (0)
; #define PG8_WAIT_V(n) asm volatile("s_waitcnt vmcnt(" #n ")" ::: "memory")
; #define PG8_BAR __builtin_amdgcn_s_barrier()
; template <class Epi, class Sched, int LDA, int LDB, bool ALIGN_EPI = true>
; __device__ __forceinline__ void gemm_phase(LAS unsigned char* lds, const Gemm g, const Sched& S, const Epi& E, int wave) {
;     ...
;     const char* cA = (const char*)g.A + (size_t)cur.pm * tstepA + (size_t)cur.kofs * 2; const char* cB = (const char*)g.Bt + (size_t)cur.pn * tstepB + (size_t)cur.kofs * 2;
;     PG8_STAGE(PG8_SB(0, 0), cB, voffB); PG8_STAGE(PG8_SB(0, 1), cB + hstepB, voffB); PG8_STAGE(PG8_SA(0, 0), cA, voffA); PG8_STAGE(PG8_SA(0, 1), cA + hstepA, voffA);
;     if (wr == 1) PG8_BAR;
;     PG8_WAIT_V(2); PG8_BAR;
;     PG8_STAGE(PG8_SB(1, 0), cB + kstep, voffB); PG8_STAGE(PG8_SA(1, 0), cA + kstep, voffA); PG8_STAGE(PG8_SB(1, 1), cB + hstepB + kstep, voffB);
;     PG8_WAIT_V(6); PG8_BAR;
.LBB0_2541:
	v_and_b32_e32 v143, 15, v0
	v_readlane_b32 s8, v252, 8
	v_bfe_u32 v18, v0, 4, 2
	v_lshlrev_b32_e32 v21, 4, v18
	v_or_b32_e32 v19, s8, v143
	v_lshlrev_b32_e32 v20, 6, v19
	s_movk_i32 s8, 0x3c0
	v_lshlrev_b32_e32 v19, 2, v19
	v_and_or_b32 v20, v20, s8, v21
	v_and_b32_e32 v19, 32, v19
	v_readlane_b32 s8, v252, 9
	v_lshl_add_u64 v[2:3], v[2:3], 0, s[72:73]
	s_add_i32 m0, s28, 0x18000
	v_bitop3_b32 v19, v20, s8, v19 bitop3:0xde
	v_lshl_or_b32 v20, v143, 6, v21
	v_lshlrev_b32_e32 v21, 2, v0
	v_and_b32_e32 v21, 32, v21
	v_readlane_b32 s8, v252, 46
	s_nop 1
	global_load_lds_dwordx4 v[2:3], off
	v_lshl_add_u64 v[2:3], v[4:5], 0, s[72:73]
	s_add_i32 m0, s28, 0x1a000
	s_add_i32 s36, s28, 0x8000
	s_add_i32 s37, s28, 0xa000
	v_bitop3_b32 v154, v20, s8, v21 bitop3:0xde
	global_load_lds_dwordx4 v[2:3], off
	v_lshl_add_u64 v[2:3], v[6:7], 0, s[72:73]
	s_mov_b32 m0, s36
	s_add_u32 s8, s2, 0x30080
	global_load_lds_dwordx4 v[2:3], off
	v_lshl_add_u64 v[2:3], v[8:9], 0, s[72:73]
	s_mov_b32 m0, s37
	s_addc_u32 s9, s3, 0
	global_load_lds_dwordx4 v[2:3], off
	v_lshl_add_u64 v[2:3], s[8:9], 0, v[136:137]
	s_add_i32 m0, s28, 0x1c000
	v_lshlrev_b32_e32 v0, 1, v0
	global_load_lds_dwordx4 v[2:3], off
	v_lshl_add_u64 v[2:3], s[8:9], 0, v[140:141]
	s_add_i32 m0, s28, 0x1e000
	v_and_b32_e32 v0, 32, v0
	global_load_lds_dwordx4 v[2:3], off
	s_waitcnt vmcnt(8)
	s_barrier
	v_readlane_b32 s10, v254, 20
	s_movk_i32 s13, 0x300
	v_lshrrev_b32_e32 v2, 1, v10
	v_add_u32_e32 v155, s10, v0
	v_mul_lo_u32 v0, v12, s13
	s_movk_i32 s12, 0x3000
	v_mad_u64_u32 v[2:3], s[10:11], v2, s12, v[0:1]
	v_or_b32_e32 v0, v2, v11
	v_add_lshl_u32 v0, v0, v13, 1
	s_mov_b64 s[14:15], 0x30080
	v_lshl_add_u64 v[144:145], v[0:1], 0, s[14:15]
	v_lshrrev_b32_e32 v2, 1, v14
	v_mul_lo_u32 v0, v16, s13
	v_readlane_b32 s8, v252, 45
	v_mad_u64_u32 v[2:3], s[10:11], v2, s12, v[0:1]
	s_waitcnt vmcnt(6)
	s_nop 0
	v_lshl_or_b32 v142, v18, 3, s8
	s_ashr_i32 s38, s19, 31
	s_ashr_i32 s39, s4, 31
	v_readlane_b32 s8, v252, 54
	v_or_b32_e32 v0, v2, v15
	s_add_u32 s8, s8, s18
	v_readlane_b32 s9, v252, 55
	v_add_lshl_u32 v0, v0, v17, 1
	v_cmp_gt_u32_e64 s[42:43], 2, v18
	s_addc_u32 s9, s9, 0
	v_lshl_add_u64 v[146:147], v[0:1], 0, s[14:15]
	s_mov_b32 s52, 0
	v_add_u32_e32 v156, 0, v19
	s_barrier
	s_branch .LBB0_2544

; #define PG8_STAGE(bufoff, gbase, voff) do { _Pragma("unroll") for (int _i = 0; _i < 2; ++_i) \
;         __builtin_amdgcn_global_load_lds((const unsigned*)((const char*)(gbase) + (voff)[_i]), (LAS unsigned*)(lds + (bufoff) + ldsw + _i * 8192), 16, 0, 0); } while (0)
; #define PG8_WAIT_V(n) asm volatile("s_waitcnt vmcnt(" #n ")" ::: "memory")
; #define PG8_BAR __builtin_amdgcn_s_barrier()
; template <class Epi, class Sched, int LDA, int LDB, bool ALIGN_EPI = true>
; __device__ __forceinline__ void gemm_phase(LAS unsigned char* lds, const Gemm g, const Sched& S, const Epi& E, int wave) {
;     ...
;     const char* cA = (const char*)g.A + (size_t)cur.pm * tstepA + (size_t)cur.kofs * 2; const char* cB = (const char*)g.Bt + (size_t)cur.pn * tstepB + (size_t)cur.kofs * 2;
;     PG8_STAGE(PG8_SB(0, 0), cB, voffB); PG8_STAGE(PG8_SB(0, 1), cB + hstepB, voffB); PG8_STAGE(PG8_SA(0, 0), cA, voffA); PG8_STAGE(PG8_SA(0, 1), cA + hstepA, voffA);
;     if (wr == 1) PG8_BAR;
;     PG8_WAIT_V(2); PG8_BAR;
;     PG8_STAGE(PG8_SB(1, 0), cB + kstep, voffB); PG8_STAGE(PG8_SA(1, 0), cA + kstep, voffA); PG8_STAGE(PG8_SB(1, 1), cB + hstepB + kstep, voffB);
;     PG8_WAIT_V(6); PG8_BAR;
.LBB0_2609:
	s_sext_i32_i8 s50, s0
	v_and_b32_e32 v16, 15, v15
	v_readlane_b32 s0, v252, 8
	v_lshrrev_b32_e32 v17, 1, v15
	v_and_b32_e32 v17, 24, v17
	v_or_b32_e32 v139, s0, v16
	v_lshlrev_b32_e32 v18, 6, v139
	v_lshlrev_b32_e32 v19, 1, v17
	s_movk_i32 s0, 0x3c0
	v_lshlrev_b32_e32 v20, 2, v139
	v_and_or_b32 v18, v18, s0, v19
	v_and_b32_e32 v20, 32, v20
	v_readlane_b32 s0, v252, 9
	v_lshlrev_b32_e32 v15, 2, v15
	v_lshl_or_b32 v16, v16, 6, v19
	v_bitop3_b32 v18, v18, s0, v20 bitop3:0xde
	v_and_b32_e32 v15, 32, v15
	v_readlane_b32 s0, v252, 11
	s_add_i32 m0, s36, 0x18000
	s_nop 1
	v_bitop3_b32 v150, v16, s0, v15 bitop3:0xde
	s_mov_b64 s[0:1], 0x80
	v_lshl_add_u64 v[2:3], v[2:3], 0, s[0:1]
	global_load_lds_dwordx4 v[2:3], off
	v_lshl_add_u64 v[2:3], v[4:5], 0, s[0:1]
	s_add_i32 m0, s36, 0x1a000
	s_add_i32 s46, s36, 0x8000
	global_load_lds_dwordx4 v[2:3], off
	v_lshl_add_u64 v[2:3], v[6:7], 0, s[0:1]
	s_mov_b32 m0, s46
	s_add_i32 s47, s36, 0xa000
	global_load_lds_dwordx4 v[2:3], off
	v_lshl_add_u64 v[2:3], v[8:9], 0, s[0:1]
	s_add_u32 s0, s16, 0x20080
	s_mov_b32 m0, s47
	s_addc_u32 s1, s17, 0
	global_load_lds_dwordx4 v[2:3], off
	v_lshl_add_u64 v[2:3], s[0:1], 0, v[132:133]
	s_add_i32 m0, s36, 0x1c000
	s_ashr_i32 s48, s4, 31
	global_load_lds_dwordx4 v[2:3], off
	v_lshl_add_u64 v[2:3], s[0:1], 0, v[136:137]
	s_add_i32 m0, s36, 0x1e000
	v_readlane_b32 s0, v252, 10
	global_load_lds_dwordx4 v[2:3], off
	s_waitcnt vmcnt(8)
	s_barrier
	v_lshlrev_b32_e32 v2, 13, v0
	v_and_b32_e32 v2, 0xffffc000, v2
	v_lshl_add_u32 v2, v10, 10, v2
	v_and_b32_e32 v0, 1, v0
	v_lshl_or_b32 v0, v0, 6, v2
	v_lshl_add_u32 v140, v11, 1, v0
	v_lshlrev_b32_e32 v0, 13, v12
	v_or_b32_e32 v138, s0, v17
	s_add_u32 s0, s22, s18
	v_and_b32_e32 v0, 0xffffc000, v0
	s_waitcnt vmcnt(6)
	s_addc_u32 s1, s23, 0
	v_lshl_add_u32 v0, v13, 10, v0
	v_and_b32_e32 v2, 1, v12
	s_add_u32 s0, s0, 0x88800
	v_lshl_or_b32 v0, v2, 6, v0
	s_addc_u32 s1, s1, 0
	v_mov_b32_e32 v141, v1
	v_lshl_add_u32 v142, v14, 1, v0
	v_mov_b32_e32 v143, v1
	s_mov_b32 s49, 0
	v_add_u32_e32 v151, 0, v18
	s_barrier
	s_branch .LBB0_2612

; #define PG8_STAGE(bufoff, gbase, voff) do { _Pragma("unroll") for (int _i = 0; _i < 2; ++_i) \
;         __builtin_amdgcn_global_load_lds((const unsigned*)((const char*)(gbase) + (voff)[_i]), (LAS unsigned*)(lds + (bufoff) + ldsw + _i * 8192), 16, 0, 0); } while (0)
; #define PG8_WAIT_V(n) asm volatile("s_waitcnt vmcnt(" #n ")" ::: "memory")
; #define PG8_BAR __builtin_amdgcn_s_barrier()
; template <class Epi, class Sched, int LDA, int LDB, bool ALIGN_EPI = true>
; __device__ __forceinline__ void gemm_phase(LAS unsigned char* lds, const Gemm g, const Sched& S, const Epi& E, int wave) {
;     ...
;     const char* cA = (const char*)g.A + (size_t)cur.pm * tstepA + (size_t)cur.kofs * 2; const char* cB = (const char*)g.Bt + (size_t)cur.pn * tstepB + (size_t)cur.kofs * 2;
;     PG8_STAGE(PG8_SB(0, 0), cB, voffB); PG8_STAGE(PG8_SB(0, 1), cB + hstepB, voffB); PG8_STAGE(PG8_SA(0, 0), cA, voffA); PG8_STAGE(PG8_SA(0, 1), cA + hstepA, voffA);
;     if (wr == 1) PG8_BAR;
;     PG8_WAIT_V(2); PG8_BAR;
;     PG8_STAGE(PG8_SB(1, 0), cB + kstep, voffB); PG8_STAGE(PG8_SA(1, 0), cA + kstep, voffA); PG8_STAGE(PG8_SB(1, 1), cB + hstepB + kstep, voffB);
;     PG8_WAIT_V(6); PG8_BAR;
.LBB0_2639:
	v_and_b32_e32 v17, 15, v16
	v_readlane_b32 s2, v252, 8
	v_lshrrev_b32_e32 v18, 1, v16
	s_mul_i32 s0, s68, 0x2200
	s_mov_b32 s1, s97
	v_or_b32_e32 v160, s2, v17
	v_and_b32_e32 v18, 24, v18
	s_lshl_b64 s[0:1], s[0:1], 2
	v_lshlrev_b32_e32 v19, 6, v160
	v_lshlrev_b32_e32 v20, 1, v18
	s_movk_i32 s2, 0x3c0
	v_lshlrev_b32_e32 v21, 2, v160
	s_add_u32 s0, s22, s0
	v_and_or_b32 v19, v19, s2, v20
	v_and_b32_e32 v21, 32, v21
	v_readlane_b32 s2, v252, 9
	v_lshlrev_b32_e32 v16, 2, v16
	s_addc_u32 s1, s23, s1
	v_bitop3_b32 v19, v19, s2, v21 bitop3:0xde
	v_lshl_or_b32 v17, v17, 6, v20
	v_and_b32_e32 v16, 32, v16
	v_readlane_b32 s2, v252, 11
	s_add_u32 s0, s0, 0x88800
	s_addc_u32 s1, s1, 0
	v_bitop3_b32 v161, v17, s2, v16 bitop3:0xde
	s_mov_b64 s[2:3], 0x80
	v_lshl_add_u64 v[2:3], v[2:3], 0, s[2:3]
	s_add_i32 m0, s15, 0x18000
	s_nop 1
	global_load_lds_dwordx4 v[2:3], off
	v_lshl_add_u64 v[2:3], v[4:5], 0, s[2:3]
	s_add_i32 m0, s15, 0x1a000
	s_add_i32 s35, s15, 0x8000
	global_load_lds_dwordx4 v[2:3], off
	v_lshl_add_u64 v[2:3], v[6:7], 0, s[2:3]
	s_mov_b32 m0, s35
	s_add_i32 s36, s15, 0xa000
	global_load_lds_dwordx4 v[2:3], off
	v_lshl_add_u64 v[2:3], v[8:9], 0, s[2:3]
	s_add_u32 s2, s18, 0x20080
	s_mov_b32 m0, s36
	s_addc_u32 s3, s19, 0
	global_load_lds_dwordx4 v[2:3], off
	v_lshl_add_u64 v[2:3], s[2:3], 0, v[0:1]
	s_add_i32 m0, s15, 0x1c000
	s_ashr_i32 s37, s5, 31
	global_load_lds_dwordx4 v[2:3], off
	v_lshl_add_u64 v[2:3], s[2:3], 0, v[142:143]
	s_add_i32 m0, s15, 0x1e000
	v_readlane_b32 s2, v252, 10
	global_load_lds_dwordx4 v[2:3], off
	s_waitcnt vmcnt(8)
	s_barrier
	v_lshlrev_b32_e32 v2, 13, v10
	v_and_b32_e32 v2, 0xffffc000, v2
	v_lshl_add_u32 v2, v11, 10, v2
	v_and_b32_e32 v3, 1, v10
	v_lshl_or_b32 v2, v3, 6, v2
	v_lshl_add_u32 v144, v12, 1, v2
	v_lshlrev_b32_e32 v2, 13, v13
	v_and_b32_e32 v2, 0xffffc000, v2
	s_waitcnt vmcnt(6)
	v_lshl_add_u32 v2, v14, 10, v2
	v_and_b32_e32 v3, 1, v13
	v_lshl_or_b32 v2, v3, 6, v2
	s_ashr_i32 s38, s4, 31
	v_or_b32_e32 v162, s2, v18
	v_mov_b32_e32 v145, v1
	v_lshl_add_u32 v146, v15, 1, v2
	v_mov_b32_e32 v147, v1
	s_mov_b32 s39, 0
	v_add_u32_e32 v163, 0, v19
	s_barrier
	s_branch .LBB0_2642

; #define PG8_STAGE(bufoff, gbase, voff) do { _Pragma("unroll") for (int _i = 0; _i < 2; ++_i) \
;         __builtin_amdgcn_global_load_lds((const unsigned*)((const char*)(gbase) + (voff)[_i]), (LAS unsigned*)(lds + (bufoff) + ldsw + _i * 8192), 16, 0, 0); } while (0)
; #define PG8_WAIT_V(n) asm volatile("s_waitcnt vmcnt(" #n ")" ::: "memory")
; #define PG8_BAR __builtin_amdgcn_s_barrier()
; template <class Epi, class Sched, int LDA, int LDB, bool ALIGN_EPI = true>
; __device__ __forceinline__ void gemm_phase(LAS unsigned char* lds, const Gemm g, const Sched& S, const Epi& E, int wave) {
;     ...
;     const char* cA = (const char*)g.A + (size_t)cur.pm * tstepA + (size_t)cur.kofs * 2; const char* cB = (const char*)g.Bt + (size_t)cur.pn * tstepB + (size_t)cur.kofs * 2;
;     PG8_STAGE(PG8_SB(0, 0), cB, voffB); PG8_STAGE(PG8_SB(0, 1), cB + hstepB, voffB); PG8_STAGE(PG8_SA(0, 0), cA, voffA); PG8_STAGE(PG8_SA(0, 1), cA + hstepA, voffA);
;     if (wr == 1) PG8_BAR;
;     PG8_WAIT_V(2); PG8_BAR;
;     PG8_STAGE(PG8_SB(1, 0), cB + kstep, voffB); PG8_STAGE(PG8_SA(1, 0), cA + kstep, voffA); PG8_STAGE(PG8_SB(1, 1), cB + hstepB + kstep, voffB);
;     PG8_WAIT_V(6); PG8_BAR;
.LBB0_4697:
	v_and_b32_e32 v16, 15, v0
	v_readlane_b32 s0, v252, 8
	v_lshrrev_b32_e32 v17, 1, v0
	v_and_b32_e32 v17, 24, v17
	v_or_b32_e32 v152, s0, v16
	v_lshlrev_b32_e32 v18, 6, v152
	v_lshlrev_b32_e32 v19, 1, v17
	s_movk_i32 s0, 0x3c0
	v_lshlrev_b32_e32 v20, 2, v152
	v_and_or_b32 v18, v18, s0, v19
	v_and_b32_e32 v20, 32, v20
	v_readlane_b32 s0, v252, 9
	v_lshlrev_b32_e32 v0, 2, v0
	v_lshl_or_b32 v16, v16, 6, v19
	v_bitop3_b32 v18, v18, s0, v20 bitop3:0xde
	v_and_b32_e32 v0, 32, v0
	v_readlane_b32 s0, v252, 11
	s_add_i32 m0, s27, 0x18000
	s_nop 1
	v_bitop3_b32 v153, v16, s0, v0 bitop3:0xde
	s_mov_b64 s[0:1], 0x80
	v_lshl_add_u64 v[2:3], v[2:3], 0, s[0:1]
	global_load_lds_dwordx4 v[2:3], off
	v_lshl_add_u64 v[2:3], v[4:5], 0, s[0:1]
	s_add_i32 m0, s27, 0x1a000
	s_add_i32 s37, s27, 0x8000
	global_load_lds_dwordx4 v[2:3], off
	v_lshl_add_u64 v[2:3], v[6:7], 0, s[0:1]
	s_mov_b32 m0, s37
	s_add_i32 s38, s27, 0xa000
	global_load_lds_dwordx4 v[2:3], off
	v_lshl_add_u64 v[2:3], v[8:9], 0, s[0:1]
	s_add_u32 s0, s24, 0x80080
	s_mov_b32 m0, s38
	s_addc_u32 s1, s25, 0
	global_load_lds_dwordx4 v[2:3], off
	v_lshl_add_u64 v[2:3], s[0:1], 0, v[132:133]
	s_add_i32 m0, s27, 0x1c000
	v_lshlrev_b32_e32 v0, 8, v152
	global_load_lds_dwordx4 v[2:3], off
	v_lshl_add_u64 v[2:3], s[0:1], 0, v[136:137]
	s_add_i32 m0, s27, 0x1e000
	v_readlane_b32 s0, v252, 56
	global_load_lds_dwordx4 v[2:3], off
	s_waitcnt vmcnt(8)
	s_barrier
	v_and_b32_e32 v0, 0xcf00, v0
	v_readlane_b32 s1, v252, 57
	v_and_b32_e32 v2, 1, v10
	s_waitcnt vmcnt(6)
	s_mul_i32 s39, s6, 3
	v_lshl_add_u64 v[138:139], s[0:1], 0, v[0:1]
	v_lshlrev_b32_e32 v0, 15, v10
	v_and_b32_e32 v0, 0xffff0000, v0
	v_lshl_add_u32 v0, v11, 12, v0
	v_lshl_or_b32 v0, v2, 6, v0
	v_lshl_add_u32 v140, v12, 1, v0
	v_lshlrev_b32_e32 v0, 15, v13
	v_and_b32_e32 v0, 0xffff0000, v0
	v_lshl_add_u32 v0, v14, 12, v0
	v_and_b32_e32 v2, 1, v13
	v_readlane_b32 s0, v252, 10
	v_lshl_or_b32 v0, v2, 6, v0
	v_mov_b32_e32 v141, v1
	v_or_b32_e32 v154, s0, v17
	v_lshl_add_u32 v142, v15, 1, v0
	v_mov_b32_e32 v143, v1
	s_mov_b32 s46, 0
	v_add_u32_e32 v155, 0, v18
	s_barrier
	s_branch .LBB0_4700

; #define PG8_STAGE(bufoff, gbase, voff) do { _Pragma("unroll") for (int _i = 0; _i < 2; ++_i) \
;         __builtin_amdgcn_global_load_lds((const unsigned*)((const char*)(gbase) + (voff)[_i]), (LAS unsigned*)(lds + (bufoff) + ldsw + _i * 8192), 16, 0, 0); } while (0)
; #define PG8_WAIT_V(n) asm volatile("s_waitcnt vmcnt(" #n ")" ::: "memory")
; #define PG8_BAR __builtin_amdgcn_s_barrier()
; template <class Epi, class Sched, int LDA, int LDB, bool ALIGN_EPI = true>
; __device__ __forceinline__ void gemm_phase(LAS unsigned char* lds, const Gemm g, const Sched& S, const Epi& E, int wave) {
;     ...
;     const char* cA = (const char*)g.A + (size_t)cur.pm * tstepA + (size_t)cur.kofs * 2; const char* cB = (const char*)g.Bt + (size_t)cur.pn * tstepB + (size_t)cur.kofs * 2;
;     PG8_STAGE(PG8_SB(0, 0), cB, voffB); PG8_STAGE(PG8_SB(0, 1), cB + hstepB, voffB); PG8_STAGE(PG8_SA(0, 0), cA, voffA); PG8_STAGE(PG8_SA(0, 1), cA + hstepA, voffA);
;     if (wr == 1) PG8_BAR;
;     PG8_WAIT_V(2); PG8_BAR;
;     PG8_STAGE(PG8_SB(1, 0), cB + kstep, voffB); PG8_STAGE(PG8_SA(1, 0), cA + kstep, voffA); PG8_STAGE(PG8_SB(1, 1), cB + hstepB + kstep, voffB);
;     PG8_WAIT_V(6); PG8_BAR;
.LBB0_4886:
	v_readlane_b32 s0, v254, 60
	v_readlane_b32 s10, v254, 62
	v_readlane_b32 s1, v254, 61
	v_readlane_b32 s11, v254, 63
	s_add_u32 s47, s10, 0xa000
	s_mul_i32 s2, s0, 3
	s_mov_b32 s1, s97
	s_mulk_i32 s0, 0x1800
	v_readlane_b32 s64, v250, 10
	s_addc_u32 s48, s11, 0
	s_lshl_b64 s[0:1], s[0:1], 2
	v_readlane_b32 s76, v250, 22
	v_readlane_b32 s77, v250, 23
	s_add_u32 s0, s76, s0
	s_addc_u32 s1, s77, s1
	s_add_u32 s0, s0, 0x4000
	s_addc_u32 s1, s1, 0
	s_add_u32 s49, s10, 0xc000
	s_addc_u32 s50, s11, 0
	s_add_i32 s8, s2, 1
	v_and_b32_e32 v17, 15, v10
	v_readlane_b32 s2, v252, 8
	v_bfe_u32 v18, v10, 4, 2
	v_lshlrev_b32_e32 v20, 4, v18
	v_or_b32_e32 v212, s2, v17
	v_lshlrev_b32_e32 v19, 6, v212
	s_movk_i32 s2, 0x3c0
	v_lshlrev_b32_e32 v21, 2, v212
	v_and_or_b32 v19, v19, s2, v20
	v_and_b32_e32 v21, 32, v21
	v_readlane_b32 s2, v252, 9
	v_lshlrev_b32_e32 v10, 2, v10
	v_lshl_or_b32 v17, v17, 6, v20
	v_bitop3_b32 v19, v19, s2, v21 bitop3:0xde
	v_and_b32_e32 v10, 32, v10
	v_readlane_b32 s2, v252, 11
	s_add_i32 m0, s27, 0x18000
	s_nop 1
	v_bitop3_b32 v213, v17, s2, v10 bitop3:0xde
	s_mov_b64 s[2:3], 0x80
	v_lshl_add_u64 v[2:3], v[2:3], 0, s[2:3]
	global_load_lds_dwordx4 v[2:3], off
	v_lshl_add_u64 v[2:3], v[4:5], 0, s[2:3]
	s_add_i32 m0, s27, 0x1a000
	s_add_i32 s51, s27, 0x8000
	global_load_lds_dwordx4 v[2:3], off
	v_lshl_add_u64 v[2:3], v[6:7], 0, s[2:3]
	s_mov_b32 m0, s51
	s_add_i32 s52, s27, 0xa000
	global_load_lds_dwordx4 v[2:3], off
	v_lshl_add_u64 v[2:3], v[8:9], 0, s[2:3]
	s_add_u32 s2, s36, 0x80080
	s_mov_b32 m0, s52
	s_addc_u32 s3, s37, 0
	global_load_lds_dwordx4 v[2:3], off
	v_lshl_add_u64 v[2:3], s[2:3], 0, v[0:1]
	s_add_i32 m0, s27, 0x1c000
	v_readlane_b32 s78, v250, 24
	global_load_lds_dwordx4 v[2:3], off
	v_lshl_add_u64 v[2:3], s[2:3], 0, v[150:151]
	s_add_i32 m0, s27, 0x1e000
	s_lshl_b32 s2, s8, 15
	global_load_lds_dwordx4 v[2:3], off
	s_waitcnt vmcnt(8)
	s_barrier
	v_lshlrev_b32_e32 v2, 15, v11
	v_and_b32_e32 v2, 0xffff0000, v2
	v_lshl_add_u32 v2, v12, 12, v2
	v_and_b32_e32 v3, 1, v11
	v_lshl_or_b32 v2, v3, 6, v2
	v_lshl_add_u32 v152, v13, 1, v2
	v_lshlrev_b32_e32 v2, 15, v14
	v_readlane_b32 s3, v252, 41
	v_and_b32_e32 v2, 0xffff0000, v2
	v_readlane_b32 s79, v250, 25
	s_waitcnt vmcnt(6)
	s_add_u32 s2, s3, s2
	v_readlane_b32 s3, v252, 42
	v_lshl_add_u32 v2, v15, 12, v2
	v_and_b32_e32 v3, 1, v14
	v_readlane_b32 s68, v250, 14
	s_addc_u32 s3, s3, 0
	s_lshl_b32 s54, s8, 5
	v_readlane_b32 s8, v252, 10
	v_lshl_or_b32 v2, v3, 6, v2
	v_readlane_b32 s78, v254, 49
	s_mov_b32 s53, 0
	v_cmp_eq_u32_e64 s[40:41], 0, v18
	v_lshl_or_b32 v214, v18, 3, s8
	v_mov_b32_e32 v153, v1
	v_lshl_add_u32 v154, v16, 1, v2
	v_mov_b32_e32 v155, v1
	v_add_u32_e32 v215, 0, v19
	v_readlane_b32 s79, v254, 50
	s_mov_b32 s68, s9
	v_readlane_b32 s65, v250, 11
	v_readlane_b32 s66, v250, 12
	v_readlane_b32 s67, v250, 13
	v_readlane_b32 s69, v250, 15
	v_readlane_b32 s70, v250, 16
	v_readlane_b32 s71, v250, 17
	v_readlane_b32 s72, v250, 18
	v_readlane_b32 s73, v250, 19
	v_readlane_b32 s74, v250, 20
	v_readlane_b32 s75, v250, 21
	s_barrier
	s_branch .LBB0_4889
